# GEMM worker workgroups start each GEMM phase staggered by (bx&3)*d (s_sleep) so epilogue bursts of different XCD groups do not coincide
# baseline (speedup 1.0000x reference)
.LBB0_210:
	s_and_b64 vcc, exec, s[0:1]
	s_cbranch_vccz .LBB0_552
	s_cmpk_lt_i32 s92, 0x420
	s_cselect_b64 s[0:1], -1, 0
	s_cmpk_gt_i32 s92, 0x41f
	v_readfirstlane_b32 s2, v0
	s_cbranch_scc1 .LBB0_213
	s_and_b32 s3, s92, 3
	s_cmp_eq_u32 s3, 0
	s_cbranch_scc1 .Lstag_done_P2
.Lstag_loop_P2:
	s_sleep 90
	s_sub_u32 s3, s3, 1
	s_cmp_lg_u32 s3, 0
	s_cbranch_scc1 .Lstag_loop_P2
.Lstag_done_P2:
	s_lshr_b32 s3, s93, 29
	s_add_i32 s3, s92, s3
	s_ashr_i32 s4, s3, 3
	s_and_b32 s3, s3, -8
	s_sub_i32 s3, s92, s3
	s_cmp_lt_i32 s3, 0
	s_movk_i32 s5, 0x85
	s_cselect_b32 s5, s5, 0x84
	s_mul_i32 s3, s3, s5
	s_add_i32 s3, s3, s4
	s_ashr_i32 s4, s3, 31
	s_lshr_b32 s4, s4, 27
	s_add_i32 s4, s3, s4
	s_ashr_i32 s5, s4, 5
	s_andn2_b32 s4, s4, 31
	s_sub_i32 s3, s3, s4
	s_bfe_i32 s4, s3, 0x80000
	s_bfe_u32 s4, s4, 0x2000d
	s_add_i32 s4, s3, s4
	s_bfe_i32 s6, s4, 0x80000
	s_and_b32 s4, s4, 0xfc
	s_sub_i32 s3, s3, s4
	s_lshl_b32 s5, s5, 2
	s_sext_i32_i16 s6, s6
	s_sext_i32_i8 s3, s3
	s_add_i32 s10, s5, s3
	s_ashr_i32 s14, s6, 2

.LBB0_1787:
	s_and_b64 vcc, exec, s[4:5]
	s_cbranch_vccz .LBB0_1837
	s_cmpk_gt_i32 s92, 0x20f
	v_readfirstlane_b32 s0, v0
	s_cbranch_scc1 .LBB0_1804
	s_and_b32 s3, s92, 3
	s_cmp_eq_u32 s3, 0
	s_cbranch_scc1 .Lstag_done_P5
.Lstag_loop_P5:
	s_sleep 85
	s_sub_u32 s3, s3, 1
	s_cmp_lg_u32 s3, 0
	s_cbranch_scc1 .Lstag_loop_P5
.Lstag_done_P5:
	v_and_b32_e32 v1, 32, v0
	v_bfe_u32 v12, v0, 2, 4
	v_bitop3_b32 v10, v148, v1, 48 bitop3:0x6c
	v_and_b32_e32 v11, 64, v0
	v_lshrrev_b32_e32 v2, 3, v0
	v_or_b32_e32 v1, v10, v11
	v_and_or_b32 v2, v2, 48, v12
	v_or_b32_e32 v13, 0x2000, v148
	v_lshl_or_b32 v136, v2, 11, v1
	v_lshrrev_b32_e32 v2, 7, v13
	s_movk_i32 s3, 0x70
	v_and_or_b32 v2, v2, s3, v12
	s_lshr_b32 s3, s93, 29
	s_add_i32 s3, s92, s3
	s_lshr_b32 s1, s0, 6
	s_ashr_i32 s4, s3, 3
	s_and_b32 s3, s3, -8
	s_lshr_b32 s2, s0, 8
	s_lshl_b32 s43, s1, 10
	s_sub_i32 s3, s92, s3
	s_cmp_lt_i32 s3, 0
	s_movk_i32 s72, 0x43
	s_cselect_b32 s5, s72, 0x42
	s_mul_i32 s3, s3, s5
	s_add_i32 s3, s3, s4
	s_ashr_i32 s4, s3, 31
	s_lshr_b32 s4, s4, 28
	s_add_i32 s4, s3, s4
	s_ashr_i32 s5, s4, 4
	s_and_b32 s4, s4, -16
	s_sub_i32 s3, s3, s4
	s_bfe_i32 s4, s3, 0x80000
	s_bfe_u32 s4, s4, 0x2000d
	s_add_i32 s6, s3, s4
	s_bfe_i32 s4, s6, 0x80000
	s_and_b32 s6, s6, 0xfc
	s_sub_i32 s3, s3, s6
	s_lshl_b32 s5, s5, 2
	s_sext_i32_i16 s4, s4
	s_sext_i32_i8 s3, s3
	s_lshr_b32 s4, s4, 2
	s_add_i32 s64, s5, s3
	s_ashr_i32 s65, s64, 31
	s_bfe_i64 s[8:9], s[4:5], 0x100000
	s_lshl_b64 s[6:7], s[64:65], 19
	s_lshl_b64 s[8:9], s[8:9], 19
	v_readlane_b32 s10, v242, 32
	v_readlane_b32 s11, v242, 33
	s_add_u32 s68, s10, s8
	s_addc_u32 s69, s11, s9
	s_add_i32 s73, s43, 0
	s_add_i32 m0, s73, 0x10000
	v_lshl_or_b32 v138, v2, 11, v1
	global_load_lds_dwordx4 v136, s[68:69]
	s_add_i32 m0, s73, 0x12000
	s_add_u32 s8, s68, 0x40000
	global_load_lds_dwordx4 v138, s[68:69]
	s_addc_u32 s9, s69, 0
	s_add_i32 m0, s73, 0x14000
	v_mov_b32_e32 v137, 0
	global_load_lds_dwordx4 v136, s[8:9]
	s_add_i32 m0, s73, 0x16000
	v_mov_b32_e32 v139, v137
	global_load_lds_dwordx4 v138, s[8:9]
	v_readlane_b32 s8, v241, 16
	v_readlane_b32 s9, v241, 17
	s_add_u32 s66, s8, s6
	s_addc_u32 s67, s9, s7
	s_add_i32 s74, s73, 0x2000
	s_mov_b32 m0, s73
	s_add_u32 s6, s66, 0x40000
	global_load_lds_dwordx4 v136, s[66:67]
	s_mov_b32 m0, s74
	s_addc_u32 s7, s67, 0
	s_add_i32 s75, s73, 0x4000
	global_load_lds_dwordx4 v138, s[66:67]
	s_mov_b32 m0, s75
	s_add_i32 s76, s73, 0x6000
	global_load_lds_dwordx4 v136, s[6:7]
	s_mov_b32 m0, s76
	s_cmp_eq_u32 s2, 1
	global_load_lds_dwordx4 v138, s[6:7]
	s_mov_b32 s77, 0
	v_lshl_add_u64 v[8:9], s[68:69], 0, v[136:137]
	v_lshl_add_u64 v[6:7], s[68:69], 0, v[138:139]
	v_lshl_add_u64 v[4:5], s[66:67], 0, v[136:137]
	v_lshl_add_u64 v[2:3], s[66:67], 0, v[138:139]
	s_cselect_b64 s[48:49], -1, 0
	s_cmp_lg_u32 s2, 1
	s_movk_i32 s78, 0x6000
	s_cbranch_scc1 .LBB0_1791
	s_barrier

.LBB0_1992:
	s_and_b64 vcc, exec, s[4:5]
	s_cbranch_vccz .LBB0_2042
	s_cmpk_gt_i32 s92, 0x83f
	v_readfirstlane_b32 s0, v0
	s_cbranch_scc1 .LBB0_2009
	s_and_b32 s4, s92, 3
	s_cmp_eq_u32 s4, 0
	s_cbranch_scc1 .Lstag_done_P7
.Lstag_loop_P7:
	s_sleep 50
	s_sub_u32 s4, s4, 1
	s_cmp_lg_u32 s4, 0
	s_cbranch_scc1 .Lstag_loop_P7
.Lstag_done_P7:
	v_lshrrev_b32_e32 v2, 1, v0
	v_and_b32_e32 v13, 24, v2
	v_lshrrev_b32_e32 v2, 5, v0
	v_and_b32_e32 v1, 32, v0
	v_and_b32_e32 v2, 4, v2
	v_bfe_u32 v3, v0, 2, 2
	v_bfe_u32 v12, v0, 2, 4
	v_bitop3_b32 v10, v148, v1, 48 bitop3:0x6c
	v_and_b32_e32 v11, 64, v0
	v_or3_b32 v2, v2, v3, v13
	v_lshrrev_b32_e32 v3, 3, v0
	v_or_b32_e32 v1, v10, v11
	v_and_or_b32 v4, v3, 48, v12
	v_and_or_b32 v3, v3, 32, v2
	v_or_b32_e32 v14, 0x2000, v148
	v_lshl_or_b32 v134, v3, 11, v1
	v_lshrrev_b32_e32 v3, 7, v14
	s_movk_i32 s4, 0x70
	v_lshl_or_b32 v132, v4, 11, v1
	v_and_or_b32 v4, v3, s4, v12
	s_movk_i32 s4, 0x60
	v_and_or_b32 v2, v3, s4, v2
	s_lshr_b32 s4, s93, 29
	s_add_i32 s4, s92, s4
	s_lshr_b32 s5, s0, 6
	s_ashr_i32 s6, s4, 3
	s_and_b32 s4, s4, -8
	s_lshr_b32 s1, s0, 8
	s_lshl_b32 s68, s5, 10
	s_sub_i32 s4, s92, s4
	s_cmp_lt_i32 s4, 0
	s_movk_i32 s69, 0x109
	s_cselect_b32 s7, s69, 0x108
	s_mul_i32 s4, s4, s7
	s_add_i32 s4, s4, s6
	s_ashr_i32 s6, s4, 31
	s_lshr_b32 s6, s6, 26
	s_add_i32 s6, s4, s6
	s_ashr_i32 s7, s6, 6
	s_andn2_b32 s6, s6, 63
	s_sub_i32 s6, s4, s6
	s_bfe_i32 s4, s6, 0x80000
	s_bfe_u32 s4, s4, 0x2000d
	s_add_i32 s8, s6, s4
	s_bfe_i32 s4, s8, 0x80000
	s_and_b32 s8, s8, 0xfc
	s_sub_i32 s6, s6, s8
	s_lshl_b32 s7, s7, 2
	s_sext_i32_i16 s4, s4
	s_sext_i32_i8 s6, s6
	s_lshr_b32 s4, s4, 2
	s_add_i32 s60, s7, s6
	s_ashr_i32 s61, s60, 31
	s_bfe_i64 s[8:9], s[4:5], 0x100000
	s_lshl_b64 s[6:7], s[60:61], 19
	s_lshl_b64 s[8:9], s[8:9], 19
	v_readlane_b32 s10, v242, 34
	v_readlane_b32 s11, v242, 35
	s_add_u32 s64, s10, s8
	s_addc_u32 s65, s11, s9
	s_add_i32 s61, s68, 0
	s_add_i32 m0, s61, 0x10000
	v_lshl_or_b32 v138, v2, 11, v1
	global_load_lds_dwordx4 v134, s[64:65]
	s_add_i32 m0, s61, 0x12000
	s_add_u32 s8, s64, 0x40000
	global_load_lds_dwordx4 v138, s[64:65]
	s_addc_u32 s9, s65, 0
	s_add_i32 m0, s61, 0x14000
	v_lshl_or_b32 v136, v4, 11, v1
	global_load_lds_dwordx4 v134, s[8:9]
	s_add_i32 m0, s61, 0x16000
	v_mov_b32_e32 v135, 0
	global_load_lds_dwordx4 v138, s[8:9]
	v_readlane_b32 s8, v242, 41
	v_readlane_b32 s9, v242, 42
	s_add_u32 s62, s8, s6
	s_addc_u32 s63, s9, s7
	s_add_i32 s70, s61, 0x2000
	s_mov_b32 m0, s61
	s_add_u32 s6, s62, 0x40000
	global_load_lds_dwordx4 v132, s[62:63]
	s_mov_b32 m0, s70
	s_addc_u32 s7, s63, 0
	s_add_i32 s71, s61, 0x4000
	global_load_lds_dwordx4 v136, s[62:63]
	s_mov_b32 m0, s71
	s_add_i32 s72, s61, 0x6000
	global_load_lds_dwordx4 v132, s[6:7]
	s_mov_b32 m0, s72
	v_mov_b32_e32 v139, v135
	global_load_lds_dwordx4 v136, s[6:7]
	v_mov_b32_e32 v133, v135
	v_mov_b32_e32 v137, v135
	s_cmp_eq_u32 s1, 1
	s_mov_b32 s73, 0
	v_lshl_add_u64 v[8:9], s[64:65], 0, v[134:135]
	v_lshl_add_u64 v[6:7], s[64:65], 0, v[138:139]
	v_lshl_add_u64 v[2:3], s[62:63], 0, v[132:133]
	s_cselect_b64 s[42:43], -1, 0
	s_cmp_lg_u32 s1, 1
	v_lshl_add_u64 v[4:5], s[62:63], 0, v[136:137]
	s_cbranch_scc1 .LBB0_1996
	s_barrier

.LBB0_2131:
	s_and_b64 vcc, exec, s[4:5]
	s_cbranch_vccz .LBB0_2148
	s_cmpk_gt_i32 s92, 0x20f
	v_readfirstlane_b32 s0, v0
	s_cbranch_scc1 .LBB0_2148
	s_and_b32 s4, s92, 3
	s_cmp_eq_u32 s4, 0
	s_cbranch_scc1 .Lstag_done_P8
.Lstag_loop_P8:
	s_sleep 107
	s_sub_u32 s4, s4, 1
	s_cmp_lg_u32 s4, 0
	s_cbranch_scc1 .Lstag_loop_P8
.Lstag_done_P8:
	v_and_b32_e32 v1, 32, v0
	v_bfe_u32 v11, v0, 2, 4
	v_bitop3_b32 v1, v148, v1, 48 bitop3:0x6c
	v_and_b32_e32 v10, 64, v0
	v_lshrrev_b32_e32 v3, 3, v0
	v_or_b32_e32 v2, v1, v10
	v_and_or_b32 v3, v3, 48, v11
	v_or_b32_e32 v12, 0x2000, v148
	v_lshl_or_b32 v130, v3, 13, v2
	v_lshrrev_b32_e32 v3, 7, v12
	s_movk_i32 s4, 0x70
	v_and_or_b32 v3, v3, s4, v11
	s_lshr_b32 s4, s93, 29
	s_add_i32 s4, s92, s4
	s_lshr_b32 s1, s0, 6
	s_ashr_i32 s6, s4, 3
	s_and_b32 s4, s4, -8
	s_lshr_b32 s5, s0, 8
	s_lshl_b32 s30, s1, 10
	s_sub_i32 s4, s92, s4
	s_cmp_lt_i32 s4, 0
	s_movk_i32 s31, 0x43
	s_cselect_b32 s7, s31, 0x42
	s_mul_i32 s4, s4, s7
	s_add_i32 s4, s4, s6
	s_ashr_i32 s6, s4, 31
	s_lshr_b32 s6, s6, 28
	s_add_i32 s6, s4, s6
	s_ashr_i32 s7, s6, 4
	s_and_b32 s6, s6, -16
	s_sub_i32 s6, s4, s6
	s_bfe_i32 s4, s6, 0x80000
	s_bfe_u32 s4, s4, 0x2000d
	s_add_i32 s8, s6, s4
	s_bfe_i32 s4, s8, 0x80000
	s_and_b32 s8, s8, 0xfc
	s_sub_i32 s6, s8, s6
	s_sext_i32_i16 s4, s4
	s_sext_i32_i8 s6, s6
	s_lshl_b32 s7, s7, 2
	s_lshr_b32 s4, s4, 2
	s_sub_i32 s6, s6, s7
	s_mov_b32 s9, 0
	s_add_i32 s8, s6, 0x83
	s_bfe_i64 s[10:11], s[4:5], 0x100000
	s_lshl_b64 s[6:7], s[8:9], 21
	s_lshl_b64 s[10:11], s[10:11], 21
	v_readlane_b32 s12, v242, 36
	v_readlane_b32 s13, v242, 37
	s_add_u32 s26, s12, s10
	s_addc_u32 s27, s13, s11
	s_add_i32 s34, s30, 0
	s_add_i32 m0, s34, 0x10000
	v_lshl_or_b32 v132, v3, 13, v2
	global_load_lds_dwordx4 v130, s[26:27]
	s_add_i32 m0, s34, 0x12000
	s_add_u32 s10, s26, 0x100000
	global_load_lds_dwordx4 v132, s[26:27]
	s_addc_u32 s11, s27, 0
	s_add_i32 m0, s34, 0x14000
	v_mov_b32_e32 v131, 0
	global_load_lds_dwordx4 v130, s[10:11]
	s_add_i32 m0, s34, 0x16000
	s_add_u32 s6, s2, s6
	s_addc_u32 s7, s3, s7
	s_add_i32 s35, s34, 0x2000
	global_load_lds_dwordx4 v132, s[10:11]
	s_mov_b32 m0, s34
	s_add_u32 s10, s6, 0x100000
	global_load_lds_dwordx4 v130, s[6:7]
	s_mov_b32 m0, s35
	s_addc_u32 s11, s7, 0
	s_add_i32 s36, s34, 0x4000
	global_load_lds_dwordx4 v132, s[6:7]
	s_mov_b32 m0, s36
	s_add_i32 s37, s34, 0x6000
	global_load_lds_dwordx4 v130, s[10:11]
	s_mov_b32 m0, s37
	v_mov_b32_e32 v133, v131
	global_load_lds_dwordx4 v132, s[10:11]
	s_cmp_eq_u32 s5, 1
	v_lshl_add_u64 v[8:9], s[26:27], 0, v[130:131]
	v_lshl_add_u64 v[6:7], s[26:27], 0, v[132:133]
	v_lshl_add_u64 v[4:5], s[6:7], 0, v[130:131]
	v_lshl_add_u64 v[2:3], s[6:7], 0, v[132:133]
	s_cselect_b64 s[10:11], -1, 0
	s_cmp_lg_u32 s5, 1
	s_movk_i32 s38, 0x6000
	s_cbranch_scc1 .LBB0_2135
	s_barrier
